# HGRN second pass v2: staging loads coalesced (4 lanes share a 64-byte chunk), 16-byte HEADS/G accesses via permuted value-tile assignment
# speedup vs baseline: 1.0201x; 1.0050x over previous
.LBB0_672:
	s_or_b64 exec, exec, s[0:1]
	s_mov_b64 s[6:7], s[46:47]
	s_waitcnt lgkmcnt(0)
	s_barrier
	v_lshrrev_b32_e32 v1, 2, v194
	v_and_b32_e32 v2, 3, v194
	v_lshlrev_b32_e32 v0, 9, v1
	v_lshl_add_u32 v0, v2, 4, v0
	v_mul_u32_u24_e32 v2, 0x440, v2
	v_lshl_add_u32 v2, v1, 1, v2
	v_lshlrev_b32_e32 v1, 2, v1
	s_mul_i32 s0, s2, 6
	s_lshr_b32 s12, s0, 3
	s_add_i32 s0, s0, 5
	s_lshr_b32 s13, s0, 3
	s_and_b32 s40, s12, 3
	s_and_b32 s41, s13, 3
	s_cmp_eq_u32 s12, s13
	s_cselect_b32 s41, 0, s41
	s_cmp_eq_u32 s40, 0
	s_cbranch_scc1 .Lfix_iss_done0
	s_lshr_b32 s0, s12, 2
	s_lshl_b32 s1, s0, 18
	s_add_u32 s4, s46, s1
	s_addc_u32 s5, s47, 0
	s_add_u32 s4, s4, 0x4200000
	s_addc_u32 s5, s5, 0
	global_load_dwordx4 v[4:7], v0, s[4:5]
	global_load_dwordx4 v[8:11], v0, s[4:5] offset:64
	global_load_dwordx4 v[12:15], v0, s[4:5] offset:128
	global_load_dwordx4 v[16:19], v0, s[4:5] offset:192
	global_load_dwordx4 v[20:23], v0, s[4:5] offset:256
	global_load_dwordx4 v[24:27], v0, s[4:5] offset:320
	global_load_dwordx4 v[28:31], v0, s[4:5] offset:384
	global_load_dwordx4 v[32:35], v0, s[4:5] offset:448
	s_cmp_lt_u32 s40, 2
	s_cbranch_scc1 .Lfix_iss_done0
	s_add_u32 s4, s4, 0x10000
	s_addc_u32 s5, s5, 0
	global_load_dwordx4 v[36:39], v0, s[4:5]
	global_load_dwordx4 v[40:43], v0, s[4:5] offset:64
	global_load_dwordx4 v[44:47], v0, s[4:5] offset:128
	global_load_dwordx4 v[48:51], v0, s[4:5] offset:192
	global_load_dwordx4 v[52:55], v0, s[4:5] offset:256
	global_load_dwordx4 v[56:59], v0, s[4:5] offset:320
	global_load_dwordx4 v[60:63], v0, s[4:5] offset:384
	global_load_dwordx4 v[64:67], v0, s[4:5] offset:448
	s_lshl_b32 s1, s0, 11
	s_add_u32 s6, s46, s1
	s_addc_u32 s7, s47, 0
	s_add_u32 s6, s6, 0x5200200
	s_addc_u32 s7, s7, 0
	global_load_dword v100, v1, s[6:7]
	s_cmp_lt_u32 s40, 3
	s_cbranch_scc1 .Lfix_iss_done0
	s_add_u32 s4, s4, 0x10000
	s_addc_u32 s5, s5, 0
	global_load_dwordx4 v[68:71], v0, s[4:5]
	global_load_dwordx4 v[72:75], v0, s[4:5] offset:64
	global_load_dwordx4 v[76:79], v0, s[4:5] offset:128
	global_load_dwordx4 v[80:83], v0, s[4:5] offset:192
	global_load_dwordx4 v[84:87], v0, s[4:5] offset:256
	global_load_dwordx4 v[88:91], v0, s[4:5] offset:320
	global_load_dwordx4 v[92:95], v0, s[4:5] offset:384
	global_load_dwordx4 v[96:99], v0, s[4:5] offset:448
	global_load_dword v102, v1, s[6:7] offset:512
.Lfix_iss_done0:
	s_cmp_eq_u32 s41, 0
	s_cbranch_scc1 .Lfix_iss_done1
	s_lshr_b32 s0, s13, 2
	s_lshl_b32 s1, s0, 18
	s_add_u32 s4, s46, s1
	s_addc_u32 s5, s47, 0
	s_add_u32 s4, s4, 0x4200000
	s_addc_u32 s5, s5, 0
	global_load_dwordx4 v[104:107], v0, s[4:5]
	global_load_dwordx4 v[108:111], v0, s[4:5] offset:64
	global_load_dwordx4 v[112:115], v0, s[4:5] offset:128
	global_load_dwordx4 v[116:119], v0, s[4:5] offset:192
	global_load_dwordx4 v[120:123], v0, s[4:5] offset:256
	global_load_dwordx4 v[124:127], v0, s[4:5] offset:320
	global_load_dwordx4 v[128:131], v0, s[4:5] offset:384
	global_load_dwordx4 v[132:135], v0, s[4:5] offset:448
	s_cmp_lt_u32 s41, 2
	s_cbranch_scc1 .Lfix_iss_done1
	s_add_u32 s4, s4, 0x10000
	s_addc_u32 s5, s5, 0
	global_load_dwordx4 v[136:139], v0, s[4:5]
	global_load_dwordx4 v[140:143], v0, s[4:5] offset:64
	global_load_dwordx4 v[144:147], v0, s[4:5] offset:128
	global_load_dwordx4 v[148:151], v0, s[4:5] offset:192
	global_load_dwordx4 v[152:155], v0, s[4:5] offset:256
	global_load_dwordx4 v[172:175], v0, s[4:5] offset:320
	global_load_dwordx4 v[176:179], v0, s[4:5] offset:384
	global_load_dwordx4 v[180:183], v0, s[4:5] offset:448
	s_lshl_b32 s1, s0, 11
	s_add_u32 s6, s46, s1
	s_addc_u32 s7, s47, 0
	s_add_u32 s6, s6, 0x5200200
	s_addc_u32 s7, s7, 0
	global_load_dword v224, v1, s[6:7]
	s_cmp_lt_u32 s41, 3
	s_cbranch_scc1 .Lfix_iss_done1
	s_add_u32 s4, s4, 0x10000
	s_addc_u32 s5, s5, 0
	global_load_dwordx4 v[184:187], v0, s[4:5]
	global_load_dwordx4 v[188:191], v0, s[4:5] offset:64
	global_load_dwordx4 v[200:203], v0, s[4:5] offset:128
	global_load_dwordx4 v[204:207], v0, s[4:5] offset:192
	global_load_dwordx4 v[208:211], v0, s[4:5] offset:256
	global_load_dwordx4 v[212:215], v0, s[4:5] offset:320
	global_load_dwordx4 v[216:219], v0, s[4:5] offset:384
	global_load_dwordx4 v[220:223], v0, s[4:5] offset:448
	global_load_dword v226, v1, s[6:7] offset:512

.Lfix_cvt0:
	v_cvt_pk_bf16_f32 v228, v4, v5
	ds_write_b16 v2, v228
	ds_write_b16_d16_hi v2, v228 offset:272
	v_cvt_pk_bf16_f32 v229, v6, v7
	ds_write_b16 v2, v229 offset:544
	ds_write_b16_d16_hi v2, v229 offset:816
	v_cvt_pk_bf16_f32 v230, v8, v9
	ds_write_b16 v2, v230 offset:4352
	ds_write_b16_d16_hi v2, v230 offset:4624
	v_cvt_pk_bf16_f32 v231, v10, v11
	ds_write_b16 v2, v231 offset:4896
	ds_write_b16_d16_hi v2, v231 offset:5168
	v_cvt_pk_bf16_f32 v228, v12, v13
	ds_write_b16 v2, v228 offset:8704
	ds_write_b16_d16_hi v2, v228 offset:8976
	v_cvt_pk_bf16_f32 v229, v14, v15
	ds_write_b16 v2, v229 offset:9248
	ds_write_b16_d16_hi v2, v229 offset:9520
	v_cvt_pk_bf16_f32 v230, v16, v17
	ds_write_b16 v2, v230 offset:13056
	ds_write_b16_d16_hi v2, v230 offset:13328
	v_cvt_pk_bf16_f32 v231, v18, v19
	ds_write_b16 v2, v231 offset:13600
	ds_write_b16_d16_hi v2, v231 offset:13872
	v_cvt_pk_bf16_f32 v228, v20, v21
	ds_write_b16 v2, v228 offset:17408
	ds_write_b16_d16_hi v2, v228 offset:17680
	v_cvt_pk_bf16_f32 v229, v22, v23
	ds_write_b16 v2, v229 offset:17952
	ds_write_b16_d16_hi v2, v229 offset:18224
	v_cvt_pk_bf16_f32 v230, v24, v25
	ds_write_b16 v2, v230 offset:21760
	ds_write_b16_d16_hi v2, v230 offset:22032
	v_cvt_pk_bf16_f32 v231, v26, v27
	ds_write_b16 v2, v231 offset:22304
	ds_write_b16_d16_hi v2, v231 offset:22576
	v_cvt_pk_bf16_f32 v228, v28, v29
	ds_write_b16 v2, v228 offset:26112
	ds_write_b16_d16_hi v2, v228 offset:26384
	v_cvt_pk_bf16_f32 v229, v30, v31
	ds_write_b16 v2, v229 offset:26656
	ds_write_b16_d16_hi v2, v229 offset:26928
	v_cvt_pk_bf16_f32 v230, v32, v33
	ds_write_b16 v2, v230 offset:30464
	ds_write_b16_d16_hi v2, v230 offset:30736
	v_cvt_pk_bf16_f32 v231, v34, v35
	ds_write_b16 v2, v231 offset:31008
	ds_write_b16_d16_hi v2, v231 offset:31280

.Lfix_cvt1:
	v_cvt_pk_bf16_f32 v228, v104, v105
	v_add_u32_e32 v1, 0x8800, v2
	ds_write_b16 v1, v228
	ds_write_b16_d16_hi v1, v228 offset:272
	v_cvt_pk_bf16_f32 v229, v106, v107
	ds_write_b16 v1, v229 offset:544
	ds_write_b16_d16_hi v1, v229 offset:816
	v_cvt_pk_bf16_f32 v230, v108, v109
	ds_write_b16 v1, v230 offset:4352
	ds_write_b16_d16_hi v1, v230 offset:4624
	v_cvt_pk_bf16_f32 v231, v110, v111
	ds_write_b16 v1, v231 offset:4896
	ds_write_b16_d16_hi v1, v231 offset:5168
	v_cvt_pk_bf16_f32 v228, v112, v113
	ds_write_b16 v1, v228 offset:8704
	ds_write_b16_d16_hi v1, v228 offset:8976
	v_cvt_pk_bf16_f32 v229, v114, v115
	ds_write_b16 v1, v229 offset:9248
	ds_write_b16_d16_hi v1, v229 offset:9520
	v_cvt_pk_bf16_f32 v230, v116, v117
	ds_write_b16 v1, v230 offset:13056
	ds_write_b16_d16_hi v1, v230 offset:13328
	v_cvt_pk_bf16_f32 v231, v118, v119
	ds_write_b16 v1, v231 offset:13600
	ds_write_b16_d16_hi v1, v231 offset:13872
	v_cvt_pk_bf16_f32 v228, v120, v121
	ds_write_b16 v1, v228 offset:17408
	ds_write_b16_d16_hi v1, v228 offset:17680
	v_cvt_pk_bf16_f32 v229, v122, v123
	ds_write_b16 v1, v229 offset:17952
	ds_write_b16_d16_hi v1, v229 offset:18224
	v_cvt_pk_bf16_f32 v230, v124, v125
	ds_write_b16 v1, v230 offset:21760
	ds_write_b16_d16_hi v1, v230 offset:22032
	v_cvt_pk_bf16_f32 v231, v126, v127
	ds_write_b16 v1, v231 offset:22304
	ds_write_b16_d16_hi v1, v231 offset:22576
	v_cvt_pk_bf16_f32 v228, v128, v129
	ds_write_b16 v1, v228 offset:26112
	ds_write_b16_d16_hi v1, v228 offset:26384
	v_cvt_pk_bf16_f32 v229, v130, v131
	ds_write_b16 v1, v229 offset:26656
	ds_write_b16_d16_hi v1, v229 offset:26928
	v_cvt_pk_bf16_f32 v230, v132, v133
	ds_write_b16 v1, v230 offset:30464
	ds_write_b16_d16_hi v1, v230 offset:30736
	v_cvt_pk_bf16_f32 v231, v134, v135
	ds_write_b16 v1, v231 offset:31008
	ds_write_b16_d16_hi v1, v231 offset:31280
.Lfix_proc_done1:
	s_waitcnt lgkmcnt(0)
	s_barrier
	v_readfirstlane_b32 s0, v194
	s_nop 3
	s_lshr_b32 s0, s0, 6
	s_cmp_gt_u32 s0, 5
	s_cbranch_scc1 .Lfix_end
	s_mul_i32 s1, s2, 6
	s_add_i32 s1, s1, s0
	s_and_b32 s13, s1, 7
	s_lshr_b32 s1, s1, 3
	s_cmp_lg_u32 s1, s12
	s_cselect_b32 s100, 0x8800, 0
	s_and_b32 s40, s1, 3
	s_lshr_b32 s1, s1, 2
	s_mul_i32 s101, s1, 43
	s_lshr_b32 s101, s101, 8
	s_mul_i32 s41, s101, 6
	s_sub_u32 s1, s1, s41
	s_lshl_b32 s41, s101, 12
	s_lshl_b32 s101, s40, 10
	s_add_u32 s41, s41, s101
	s_lshl_b32 s101, s13, 7
	s_add_u32 s41, s41, s101
	s_lshl_b32 s1, s1, 8
	s_mul_i32 s101, s41, 0x600
	s_add_u32 s101, s101, s1
	s_add_u32 s4, s44, s101
	s_addc_u32 s5, s45, 0
	s_add_u32 s6, s46, s101
	s_addc_u32 s7, s47, 0
	s_add_u32 s6, s6, 0x13200000
	s_addc_u32 s7, s7, 0
	s_lshl_b32 s101, s41, 11
	s_add_u32 s101, s101, s1
	s_add_u32 s8, s46, s101
	s_addc_u32 s9, s47, 0
	s_add_u32 s8, s8, 0x8200000
	s_addc_u32 s9, s9, 0
	s_mov_b64 s[10:11], s[8:9]
	v_and_b32_e32 v220, 15, v197
	v_lshrrev_b32_e32 v221, 4, v197
	v_mul_u32_u24_e32 v0, 0x600, v220
	v_lshl_add_u32 v0, v221, 4, v0
	v_mov_b32_e32 v1, v0
	v_lshlrev_b32_e32 v2, 11, v220
	v_lshl_add_u32 v2, v221, 4, v2
	v_lshrrev_b32_e32 v232, 2, v220
	v_lshlrev_b32_e32 v232, 3, v232
	v_and_b32_e32 v222, 3, v220
	v_add_u32_e32 v232, v232, v222
	v_mul_u32_u24_e32 v232, 0x110, v232
	v_lshl_add_u32 v232, v221, 4, v232
	v_add_u32_e32 v232, s100, v232
	v_xor_b32_e32 v233, 16, v197
	v_xor_b32_e32 v234, 32, v197
	v_lshlrev_b32_e32 v233, 2, v233
	v_lshlrev_b32_e32 v234, 2, v234
	global_load_dwordx4 v[36:39], v0, s[4:5]
	global_load_dwordx4 v[40:43], v0, s[4:5] offset:64
	global_load_dwordx4 v[44:47], v0, s[4:5] offset:128
	global_load_dwordx4 v[48:51], v0, s[4:5] offset:192
	global_load_dwordx4 v[52:55], v2, s[8:9]
	global_load_dwordx4 v[56:59], v2, s[8:9] offset:64
	global_load_dwordx4 v[60:63], v2, s[8:9] offset:128
	global_load_dwordx4 v[64:67], v2, s[8:9] offset:192
	global_load_dwordx4 v[68:71], v1, s[6:7]
	global_load_dwordx4 v[72:75], v1, s[6:7] offset:64
	global_load_dwordx4 v[76:79], v1, s[6:7] offset:128
	global_load_dwordx4 v[80:83], v1, s[6:7] offset:192
	s_add_u32 s4, s4, 0x6000
	s_addc_u32 s5, s5, 0
	s_add_u32 s6, s6, 0x6000
	s_addc_u32 s7, s7, 0
	s_add_u32 s8, s8, 0x8000
	s_addc_u32 s9, s9, 0
	global_load_dwordx4 v[84:87], v0, s[4:5]
	global_load_dwordx4 v[88:91], v0, s[4:5] offset:64
	global_load_dwordx4 v[92:95], v0, s[4:5] offset:128
	global_load_dwordx4 v[96:99], v0, s[4:5] offset:192
	global_load_dwordx4 v[100:103], v2, s[8:9]
	global_load_dwordx4 v[104:107], v2, s[8:9] offset:64
	global_load_dwordx4 v[108:111], v2, s[8:9] offset:128
	global_load_dwordx4 v[112:115], v2, s[8:9] offset:192
	global_load_dwordx4 v[116:119], v1, s[6:7]
	global_load_dwordx4 v[120:123], v1, s[6:7] offset:64
	global_load_dwordx4 v[124:127], v1, s[6:7] offset:128
	global_load_dwordx4 v[128:131], v1, s[6:7] offset:192
	s_add_u32 s4, s4, 0x6000
	s_addc_u32 s5, s5, 0
	s_add_u32 s6, s6, 0x6000
	s_addc_u32 s7, s7, 0
	s_add_u32 s8, s8, 0x8000
	s_addc_u32 s9, s9, 0
	s_cmp_eq_u32 s40, 0
	s_cbranch_scc1 .Lfix_nomm_t0
	s_waitcnt vmcnt(20)
	ds_read_b128 v[132:135], v232 offset:0
	ds_read_b128 v[136:139], v232 offset:64
	ds_read_b128 v[140:143], v232 offset:128
	ds_read_b128 v[144:147], v232 offset:192
	ds_read_b128 v[148:151], v232 offset:1088
	ds_read_b128 v[152:155], v232 offset:1152
	ds_read_b128 v[172:175], v232 offset:1216
	ds_read_b128 v[176:179], v232 offset:1280
	ds_read_b128 v[180:183], v232 offset:8704
	ds_read_b128 v[184:187], v232 offset:8768
	ds_read_b128 v[188:191], v232 offset:8832
	ds_read_b128 v[200:203], v232 offset:8896
	s_waitcnt lgkmcnt(8)
	v_mfma_f32_16x16x32_bf16 v[4:7], v[132:135], v[36:39], 0
	v_mfma_f32_16x16x32_bf16 v[4:7], v[136:139], v[40:43], v[4:7]
	v_mfma_f32_16x16x32_bf16 v[4:7], v[140:143], v[44:47], v[4:7]
	v_mfma_f32_16x16x32_bf16 v[4:7], v[144:147], v[48:51], v[4:7]
	ds_read_b128 v[132:135], v232 offset:9792
	ds_read_b128 v[136:139], v232 offset:9856
	ds_read_b128 v[140:143], v232 offset:9920
	ds_read_b128 v[144:147], v232 offset:9984
	s_waitcnt lgkmcnt(8)
	v_mfma_f32_16x16x32_bf16 v[8:11], v[148:151], v[36:39], 0
	v_mfma_f32_16x16x32_bf16 v[8:11], v[152:155], v[40:43], v[8:11]
	v_mfma_f32_16x16x32_bf16 v[8:11], v[172:175], v[44:47], v[8:11]
	v_mfma_f32_16x16x32_bf16 v[8:11], v[176:179], v[48:51], v[8:11]
	ds_read_b128 v[148:151], v232 offset:17408
	ds_read_b128 v[152:155], v232 offset:17472
	ds_read_b128 v[172:175], v232 offset:17536
	ds_read_b128 v[176:179], v232 offset:17600
	s_waitcnt lgkmcnt(8)
	v_mfma_f32_16x16x32_bf16 v[12:15], v[180:183], v[36:39], 0
	v_mfma_f32_16x16x32_bf16 v[12:15], v[184:187], v[40:43], v[12:15]
	v_mfma_f32_16x16x32_bf16 v[12:15], v[188:191], v[44:47], v[12:15]
	v_mfma_f32_16x16x32_bf16 v[12:15], v[200:203], v[48:51], v[12:15]
	ds_read_b128 v[180:183], v232 offset:18496
	ds_read_b128 v[184:187], v232 offset:18560
	ds_read_b128 v[188:191], v232 offset:18624
	ds_read_b128 v[200:203], v232 offset:18688
	s_waitcnt lgkmcnt(8)
	v_mfma_f32_16x16x32_bf16 v[16:19], v[132:135], v[36:39], 0
	v_mfma_f32_16x16x32_bf16 v[16:19], v[136:139], v[40:43], v[16:19]
	v_mfma_f32_16x16x32_bf16 v[16:19], v[140:143], v[44:47], v[16:19]
	v_mfma_f32_16x16x32_bf16 v[16:19], v[144:147], v[48:51], v[16:19]
	ds_read_b128 v[132:135], v232 offset:26112
	ds_read_b128 v[136:139], v232 offset:26176
	ds_read_b128 v[140:143], v232 offset:26240
	ds_read_b128 v[144:147], v232 offset:26304
	s_waitcnt lgkmcnt(8)
	v_mfma_f32_16x16x32_bf16 v[20:23], v[148:151], v[36:39], 0
	v_mfma_f32_16x16x32_bf16 v[20:23], v[152:155], v[40:43], v[20:23]
	v_mfma_f32_16x16x32_bf16 v[20:23], v[172:175], v[44:47], v[20:23]
	v_mfma_f32_16x16x32_bf16 v[20:23], v[176:179], v[48:51], v[20:23]
	ds_read_b128 v[148:151], v232 offset:27200
	ds_read_b128 v[152:155], v232 offset:27264
	ds_read_b128 v[172:175], v232 offset:27328
	ds_read_b128 v[176:179], v232 offset:27392
	s_waitcnt lgkmcnt(8)
	v_mfma_f32_16x16x32_bf16 v[24:27], v[180:183], v[36:39], 0
	v_mfma_f32_16x16x32_bf16 v[24:27], v[184:187], v[40:43], v[24:27]
	v_mfma_f32_16x16x32_bf16 v[24:27], v[188:191], v[44:47], v[24:27]
	v_mfma_f32_16x16x32_bf16 v[24:27], v[200:203], v[48:51], v[24:27]
	s_waitcnt lgkmcnt(4)
	v_mfma_f32_16x16x32_bf16 v[28:31], v[132:135], v[36:39], 0
	v_mfma_f32_16x16x32_bf16 v[28:31], v[136:139], v[40:43], v[28:31]
	v_mfma_f32_16x16x32_bf16 v[28:31], v[140:143], v[44:47], v[28:31]
	v_mfma_f32_16x16x32_bf16 v[28:31], v[144:147], v[48:51], v[28:31]
	s_waitcnt lgkmcnt(0)
	v_mfma_f32_16x16x32_bf16 v[32:35], v[148:151], v[36:39], 0
	v_mfma_f32_16x16x32_bf16 v[32:35], v[152:155], v[40:43], v[32:35]
	v_mfma_f32_16x16x32_bf16 v[32:35], v[172:175], v[44:47], v[32:35]
	v_mfma_f32_16x16x32_bf16 v[32:35], v[176:179], v[48:51], v[32:35]
	s_branch .Lfix_mmdone_t0

.Lfix_mmdone_t0:
	s_waitcnt vmcnt(16)
	v_lshlrev_b32_e32 v220, 16, v52
	v_and_b32_e32 v221, 0xffff0000, v52
	v_lshlrev_b32_e32 v222, 16, v53
	v_and_b32_e32 v223, 0xffff0000, v53
	v_pk_add_f32 v[4:5], v[4:5], v[220:221]
	v_pk_add_f32 v[6:7], v[6:7], v[222:223]
	v_pk_mul_f32 v[224:225], v[4:5], v[4:5]
	v_pk_fma_f32 v[224:225], v[6:7], v[6:7], v[224:225]
	v_lshlrev_b32_e32 v220, 16, v54
	v_and_b32_e32 v221, 0xffff0000, v54
	v_lshlrev_b32_e32 v222, 16, v55
	v_and_b32_e32 v223, 0xffff0000, v55
	v_pk_add_f32 v[8:9], v[8:9], v[220:221]
	v_pk_add_f32 v[10:11], v[10:11], v[222:223]
	v_pk_fma_f32 v[224:225], v[8:9], v[8:9], v[224:225]
	v_pk_fma_f32 v[224:225], v[10:11], v[10:11], v[224:225]
	v_lshlrev_b32_e32 v220, 16, v56
	v_and_b32_e32 v221, 0xffff0000, v56
	v_lshlrev_b32_e32 v222, 16, v57
	v_and_b32_e32 v223, 0xffff0000, v57
	v_pk_add_f32 v[12:13], v[12:13], v[220:221]
	v_pk_add_f32 v[14:15], v[14:15], v[222:223]
	v_pk_fma_f32 v[224:225], v[12:13], v[12:13], v[224:225]
	v_pk_fma_f32 v[224:225], v[14:15], v[14:15], v[224:225]
	v_lshlrev_b32_e32 v220, 16, v58
	v_and_b32_e32 v221, 0xffff0000, v58
	v_lshlrev_b32_e32 v222, 16, v59
	v_and_b32_e32 v223, 0xffff0000, v59
	v_pk_add_f32 v[16:17], v[16:17], v[220:221]
	v_pk_add_f32 v[18:19], v[18:19], v[222:223]
	v_pk_fma_f32 v[224:225], v[16:17], v[16:17], v[224:225]
	v_pk_fma_f32 v[224:225], v[18:19], v[18:19], v[224:225]
	v_lshlrev_b32_e32 v220, 16, v60
	v_and_b32_e32 v221, 0xffff0000, v60
	v_lshlrev_b32_e32 v222, 16, v61
	v_and_b32_e32 v223, 0xffff0000, v61
	v_pk_add_f32 v[20:21], v[20:21], v[220:221]
	v_pk_add_f32 v[22:23], v[22:23], v[222:223]
	v_pk_fma_f32 v[224:225], v[20:21], v[20:21], v[224:225]
	v_pk_fma_f32 v[224:225], v[22:23], v[22:23], v[224:225]
	v_lshlrev_b32_e32 v220, 16, v62
	v_and_b32_e32 v221, 0xffff0000, v62
	v_lshlrev_b32_e32 v222, 16, v63
	v_and_b32_e32 v223, 0xffff0000, v63
	v_pk_add_f32 v[24:25], v[24:25], v[220:221]
	v_pk_add_f32 v[26:27], v[26:27], v[222:223]
	v_pk_fma_f32 v[224:225], v[24:25], v[24:25], v[224:225]
	v_pk_fma_f32 v[224:225], v[26:27], v[26:27], v[224:225]
	v_lshlrev_b32_e32 v220, 16, v64
	v_and_b32_e32 v221, 0xffff0000, v64
	v_lshlrev_b32_e32 v222, 16, v65
	v_and_b32_e32 v223, 0xffff0000, v65
	v_pk_add_f32 v[28:29], v[28:29], v[220:221]
	v_pk_add_f32 v[30:31], v[30:31], v[222:223]
	v_pk_fma_f32 v[224:225], v[28:29], v[28:29], v[224:225]
	v_pk_fma_f32 v[224:225], v[30:31], v[30:31], v[224:225]
	v_lshlrev_b32_e32 v220, 16, v66
	v_and_b32_e32 v221, 0xffff0000, v66
	v_lshlrev_b32_e32 v222, 16, v67
	v_and_b32_e32 v223, 0xffff0000, v67
	v_pk_add_f32 v[32:33], v[32:33], v[220:221]
	v_pk_add_f32 v[34:35], v[34:35], v[222:223]
	v_pk_fma_f32 v[224:225], v[32:33], v[32:33], v[224:225]
	v_pk_fma_f32 v[224:225], v[34:35], v[34:35], v[224:225]
	v_add_f32_e32 v226, v224, v225
	ds_bpermute_b32 v227, v233, v226
	s_waitcnt lgkmcnt(0)
	v_add_f32_e32 v226, v226, v227
	ds_bpermute_b32 v227, v234, v226
	s_waitcnt lgkmcnt(0)
	v_add_f32_e32 v226, v226, v227
	v_fmamk_f32 v226, v226, 0x3c000000, v195
	v_rsq_f32_e32 v228, v226
	s_nop 0
	s_waitcnt vmcnt(12)
	v_pk_mul_f32 v[4:5], v[4:5], v[228:229] op_sel_hi:[1,0]
	v_pk_mul_f32 v[6:7], v[6:7], v[228:229] op_sel_hi:[1,0]
	v_lshlrev_b32_e32 v220, 16, v68
	v_and_b32_e32 v221, 0xffff0000, v68
	v_lshlrev_b32_e32 v222, 16, v69
	v_and_b32_e32 v223, 0xffff0000, v69
	v_pk_mul_f32 v[4:5], v[4:5], v[220:221]
	v_pk_mul_f32 v[6:7], v[6:7], v[222:223]
	v_cvt_pk_bf16_f32 v68, v4, v5
	v_cvt_pk_bf16_f32 v69, v6, v7
	v_pk_mul_f32 v[8:9], v[8:9], v[228:229] op_sel_hi:[1,0]
	v_pk_mul_f32 v[10:11], v[10:11], v[228:229] op_sel_hi:[1,0]
	v_lshlrev_b32_e32 v220, 16, v70
	v_and_b32_e32 v221, 0xffff0000, v70
	v_lshlrev_b32_e32 v222, 16, v71
	v_and_b32_e32 v223, 0xffff0000, v71
	v_pk_mul_f32 v[8:9], v[8:9], v[220:221]
	v_pk_mul_f32 v[10:11], v[10:11], v[222:223]
	v_cvt_pk_bf16_f32 v70, v8, v9
	v_cvt_pk_bf16_f32 v71, v10, v11
	global_store_dwordx4 v2, v[68:71], s[10:11]
	v_pk_mul_f32 v[12:13], v[12:13], v[228:229] op_sel_hi:[1,0]
	v_pk_mul_f32 v[14:15], v[14:15], v[228:229] op_sel_hi:[1,0]
	v_lshlrev_b32_e32 v220, 16, v72
	v_and_b32_e32 v221, 0xffff0000, v72
	v_lshlrev_b32_e32 v222, 16, v73
	v_and_b32_e32 v223, 0xffff0000, v73
	v_pk_mul_f32 v[12:13], v[12:13], v[220:221]
	v_pk_mul_f32 v[14:15], v[14:15], v[222:223]
	v_cvt_pk_bf16_f32 v72, v12, v13
	v_cvt_pk_bf16_f32 v73, v14, v15
	v_pk_mul_f32 v[16:17], v[16:17], v[228:229] op_sel_hi:[1,0]
	v_pk_mul_f32 v[18:19], v[18:19], v[228:229] op_sel_hi:[1,0]
	v_lshlrev_b32_e32 v220, 16, v74
	v_and_b32_e32 v221, 0xffff0000, v74
	v_lshlrev_b32_e32 v222, 16, v75
	v_and_b32_e32 v223, 0xffff0000, v75
	v_pk_mul_f32 v[16:17], v[16:17], v[220:221]
	v_pk_mul_f32 v[18:19], v[18:19], v[222:223]
	v_cvt_pk_bf16_f32 v74, v16, v17
	v_cvt_pk_bf16_f32 v75, v18, v19
	global_store_dwordx4 v2, v[72:75], s[10:11] offset:64
	v_pk_mul_f32 v[20:21], v[20:21], v[228:229] op_sel_hi:[1,0]
	v_pk_mul_f32 v[22:23], v[22:23], v[228:229] op_sel_hi:[1,0]
	v_lshlrev_b32_e32 v220, 16, v76
	v_and_b32_e32 v221, 0xffff0000, v76
	v_lshlrev_b32_e32 v222, 16, v77
	v_and_b32_e32 v223, 0xffff0000, v77
	v_pk_mul_f32 v[20:21], v[20:21], v[220:221]
	v_pk_mul_f32 v[22:23], v[22:23], v[222:223]
	v_cvt_pk_bf16_f32 v76, v20, v21
	v_cvt_pk_bf16_f32 v77, v22, v23
	v_pk_mul_f32 v[24:25], v[24:25], v[228:229] op_sel_hi:[1,0]
	v_pk_mul_f32 v[26:27], v[26:27], v[228:229] op_sel_hi:[1,0]
	v_lshlrev_b32_e32 v220, 16, v78
	v_and_b32_e32 v221, 0xffff0000, v78
	v_lshlrev_b32_e32 v222, 16, v79
	v_and_b32_e32 v223, 0xffff0000, v79
	v_pk_mul_f32 v[24:25], v[24:25], v[220:221]
	v_pk_mul_f32 v[26:27], v[26:27], v[222:223]
	v_cvt_pk_bf16_f32 v78, v24, v25
	v_cvt_pk_bf16_f32 v79, v26, v27
	global_store_dwordx4 v2, v[76:79], s[10:11] offset:128
	v_pk_mul_f32 v[28:29], v[28:29], v[228:229] op_sel_hi:[1,0]
	v_pk_mul_f32 v[30:31], v[30:31], v[228:229] op_sel_hi:[1,0]
	v_lshlrev_b32_e32 v220, 16, v80
	v_and_b32_e32 v221, 0xffff0000, v80
	v_lshlrev_b32_e32 v222, 16, v81
	v_and_b32_e32 v223, 0xffff0000, v81
	v_pk_mul_f32 v[28:29], v[28:29], v[220:221]
	v_pk_mul_f32 v[30:31], v[30:31], v[222:223]
	v_cvt_pk_bf16_f32 v80, v28, v29
	v_cvt_pk_bf16_f32 v81, v30, v31
	v_pk_mul_f32 v[32:33], v[32:33], v[228:229] op_sel_hi:[1,0]
	v_pk_mul_f32 v[34:35], v[34:35], v[228:229] op_sel_hi:[1,0]
	v_lshlrev_b32_e32 v220, 16, v82
	v_and_b32_e32 v221, 0xffff0000, v82
	v_lshlrev_b32_e32 v222, 16, v83
	v_and_b32_e32 v223, 0xffff0000, v83
	v_pk_mul_f32 v[32:33], v[32:33], v[220:221]
	v_pk_mul_f32 v[34:35], v[34:35], v[222:223]
	v_cvt_pk_bf16_f32 v82, v32, v33
	v_cvt_pk_bf16_f32 v83, v34, v35
	global_store_dwordx4 v2, v[80:83], s[10:11] offset:192
	s_add_u32 s10, s10, 0x8000
	s_addc_u32 s11, s11, 0
	s_mov_b32 s13, 3
.Lfix_loop:
	global_load_dwordx4 v[36:39], v0, s[4:5]
	global_load_dwordx4 v[40:43], v0, s[4:5] offset:64
	global_load_dwordx4 v[44:47], v0, s[4:5] offset:128
	global_load_dwordx4 v[48:51], v0, s[4:5] offset:192
	global_load_dwordx4 v[52:55], v2, s[8:9]
	global_load_dwordx4 v[56:59], v2, s[8:9] offset:64
	global_load_dwordx4 v[60:63], v2, s[8:9] offset:128
	global_load_dwordx4 v[64:67], v2, s[8:9] offset:192
	global_load_dwordx4 v[68:71], v1, s[6:7]
	global_load_dwordx4 v[72:75], v1, s[6:7] offset:64
	global_load_dwordx4 v[76:79], v1, s[6:7] offset:128
	global_load_dwordx4 v[80:83], v1, s[6:7] offset:192
	s_add_u32 s4, s4, 0x6000
	s_addc_u32 s5, s5, 0
	s_add_u32 s6, s6, 0x6000
	s_addc_u32 s7, s7, 0
	s_add_u32 s8, s8, 0x8000
	s_addc_u32 s9, s9, 0
	s_cmp_eq_u32 s40, 0
	s_cbranch_scc1 .Lfix_nomm_ta
	s_waitcnt vmcnt(24)
	ds_read_b128 v[132:135], v232 offset:0
	ds_read_b128 v[136:139], v232 offset:64
	ds_read_b128 v[140:143], v232 offset:128
	ds_read_b128 v[144:147], v232 offset:192
	ds_read_b128 v[148:151], v232 offset:1088
	ds_read_b128 v[152:155], v232 offset:1152
	ds_read_b128 v[172:175], v232 offset:1216
	ds_read_b128 v[176:179], v232 offset:1280
	ds_read_b128 v[180:183], v232 offset:8704
	ds_read_b128 v[184:187], v232 offset:8768
	ds_read_b128 v[188:191], v232 offset:8832
	ds_read_b128 v[200:203], v232 offset:8896
	s_waitcnt lgkmcnt(8)
	v_mfma_f32_16x16x32_bf16 v[4:7], v[132:135], v[84:87], 0
	v_mfma_f32_16x16x32_bf16 v[4:7], v[136:139], v[88:91], v[4:7]
	v_mfma_f32_16x16x32_bf16 v[4:7], v[140:143], v[92:95], v[4:7]
	v_mfma_f32_16x16x32_bf16 v[4:7], v[144:147], v[96:99], v[4:7]
	ds_read_b128 v[132:135], v232 offset:9792
	ds_read_b128 v[136:139], v232 offset:9856
	ds_read_b128 v[140:143], v232 offset:9920
	ds_read_b128 v[144:147], v232 offset:9984
	s_waitcnt lgkmcnt(8)
	v_mfma_f32_16x16x32_bf16 v[8:11], v[148:151], v[84:87], 0
	v_mfma_f32_16x16x32_bf16 v[8:11], v[152:155], v[88:91], v[8:11]
	v_mfma_f32_16x16x32_bf16 v[8:11], v[172:175], v[92:95], v[8:11]
	v_mfma_f32_16x16x32_bf16 v[8:11], v[176:179], v[96:99], v[8:11]
	ds_read_b128 v[148:151], v232 offset:17408
	ds_read_b128 v[152:155], v232 offset:17472
	ds_read_b128 v[172:175], v232 offset:17536
	ds_read_b128 v[176:179], v232 offset:17600
	s_waitcnt lgkmcnt(8)
	v_mfma_f32_16x16x32_bf16 v[12:15], v[180:183], v[84:87], 0
	v_mfma_f32_16x16x32_bf16 v[12:15], v[184:187], v[88:91], v[12:15]
	v_mfma_f32_16x16x32_bf16 v[12:15], v[188:191], v[92:95], v[12:15]
	v_mfma_f32_16x16x32_bf16 v[12:15], v[200:203], v[96:99], v[12:15]
	ds_read_b128 v[180:183], v232 offset:18496
	ds_read_b128 v[184:187], v232 offset:18560
	ds_read_b128 v[188:191], v232 offset:18624
	ds_read_b128 v[200:203], v232 offset:18688
	s_waitcnt lgkmcnt(8)
	v_mfma_f32_16x16x32_bf16 v[16:19], v[132:135], v[84:87], 0
	v_mfma_f32_16x16x32_bf16 v[16:19], v[136:139], v[88:91], v[16:19]
	v_mfma_f32_16x16x32_bf16 v[16:19], v[140:143], v[92:95], v[16:19]
	v_mfma_f32_16x16x32_bf16 v[16:19], v[144:147], v[96:99], v[16:19]
	ds_read_b128 v[132:135], v232 offset:26112
	ds_read_b128 v[136:139], v232 offset:26176
	ds_read_b128 v[140:143], v232 offset:26240
	ds_read_b128 v[144:147], v232 offset:26304
	s_waitcnt lgkmcnt(8)
	v_mfma_f32_16x16x32_bf16 v[20:23], v[148:151], v[84:87], 0
	v_mfma_f32_16x16x32_bf16 v[20:23], v[152:155], v[88:91], v[20:23]
	v_mfma_f32_16x16x32_bf16 v[20:23], v[172:175], v[92:95], v[20:23]
	v_mfma_f32_16x16x32_bf16 v[20:23], v[176:179], v[96:99], v[20:23]
	ds_read_b128 v[148:151], v232 offset:27200
	ds_read_b128 v[152:155], v232 offset:27264
	ds_read_b128 v[172:175], v232 offset:27328
	ds_read_b128 v[176:179], v232 offset:27392
	s_waitcnt lgkmcnt(8)
	v_mfma_f32_16x16x32_bf16 v[24:27], v[180:183], v[84:87], 0
	v_mfma_f32_16x16x32_bf16 v[24:27], v[184:187], v[88:91], v[24:27]
	v_mfma_f32_16x16x32_bf16 v[24:27], v[188:191], v[92:95], v[24:27]
	v_mfma_f32_16x16x32_bf16 v[24:27], v[200:203], v[96:99], v[24:27]
	s_waitcnt lgkmcnt(4)
	v_mfma_f32_16x16x32_bf16 v[28:31], v[132:135], v[84:87], 0
	v_mfma_f32_16x16x32_bf16 v[28:31], v[136:139], v[88:91], v[28:31]
	v_mfma_f32_16x16x32_bf16 v[28:31], v[140:143], v[92:95], v[28:31]
	v_mfma_f32_16x16x32_bf16 v[28:31], v[144:147], v[96:99], v[28:31]
	s_waitcnt lgkmcnt(0)
	v_mfma_f32_16x16x32_bf16 v[32:35], v[148:151], v[84:87], 0
	v_mfma_f32_16x16x32_bf16 v[32:35], v[152:155], v[88:91], v[32:35]
	v_mfma_f32_16x16x32_bf16 v[32:35], v[172:175], v[92:95], v[32:35]
	v_mfma_f32_16x16x32_bf16 v[32:35], v[176:179], v[96:99], v[32:35]
	s_branch .Lfix_mmdone_ta

.Lfix_mmdone_ta:
	s_waitcnt vmcnt(20)
	v_lshlrev_b32_e32 v220, 16, v100
	v_and_b32_e32 v221, 0xffff0000, v100
	v_lshlrev_b32_e32 v222, 16, v101
	v_and_b32_e32 v223, 0xffff0000, v101
	v_pk_add_f32 v[4:5], v[4:5], v[220:221]
	v_pk_add_f32 v[6:7], v[6:7], v[222:223]
	v_pk_mul_f32 v[224:225], v[4:5], v[4:5]
	v_pk_fma_f32 v[224:225], v[6:7], v[6:7], v[224:225]
	v_lshlrev_b32_e32 v220, 16, v102
	v_and_b32_e32 v221, 0xffff0000, v102
	v_lshlrev_b32_e32 v222, 16, v103
	v_and_b32_e32 v223, 0xffff0000, v103
	v_pk_add_f32 v[8:9], v[8:9], v[220:221]
	v_pk_add_f32 v[10:11], v[10:11], v[222:223]
	v_pk_fma_f32 v[224:225], v[8:9], v[8:9], v[224:225]
	v_pk_fma_f32 v[224:225], v[10:11], v[10:11], v[224:225]
	v_lshlrev_b32_e32 v220, 16, v104
	v_and_b32_e32 v221, 0xffff0000, v104
	v_lshlrev_b32_e32 v222, 16, v105
	v_and_b32_e32 v223, 0xffff0000, v105
	v_pk_add_f32 v[12:13], v[12:13], v[220:221]
	v_pk_add_f32 v[14:15], v[14:15], v[222:223]
	v_pk_fma_f32 v[224:225], v[12:13], v[12:13], v[224:225]
	v_pk_fma_f32 v[224:225], v[14:15], v[14:15], v[224:225]
	v_lshlrev_b32_e32 v220, 16, v106
	v_and_b32_e32 v221, 0xffff0000, v106
	v_lshlrev_b32_e32 v222, 16, v107
	v_and_b32_e32 v223, 0xffff0000, v107
	v_pk_add_f32 v[16:17], v[16:17], v[220:221]
	v_pk_add_f32 v[18:19], v[18:19], v[222:223]
	v_pk_fma_f32 v[224:225], v[16:17], v[16:17], v[224:225]
	v_pk_fma_f32 v[224:225], v[18:19], v[18:19], v[224:225]
	v_lshlrev_b32_e32 v220, 16, v108
	v_and_b32_e32 v221, 0xffff0000, v108
	v_lshlrev_b32_e32 v222, 16, v109
	v_and_b32_e32 v223, 0xffff0000, v109
	v_pk_add_f32 v[20:21], v[20:21], v[220:221]
	v_pk_add_f32 v[22:23], v[22:23], v[222:223]
	v_pk_fma_f32 v[224:225], v[20:21], v[20:21], v[224:225]
	v_pk_fma_f32 v[224:225], v[22:23], v[22:23], v[224:225]
	v_lshlrev_b32_e32 v220, 16, v110
	v_and_b32_e32 v221, 0xffff0000, v110
	v_lshlrev_b32_e32 v222, 16, v111
	v_and_b32_e32 v223, 0xffff0000, v111
	v_pk_add_f32 v[24:25], v[24:25], v[220:221]
	v_pk_add_f32 v[26:27], v[26:27], v[222:223]
	v_pk_fma_f32 v[224:225], v[24:25], v[24:25], v[224:225]
	v_pk_fma_f32 v[224:225], v[26:27], v[26:27], v[224:225]
	v_lshlrev_b32_e32 v220, 16, v112
	v_and_b32_e32 v221, 0xffff0000, v112
	v_lshlrev_b32_e32 v222, 16, v113
	v_and_b32_e32 v223, 0xffff0000, v113
	v_pk_add_f32 v[28:29], v[28:29], v[220:221]
	v_pk_add_f32 v[30:31], v[30:31], v[222:223]
	v_pk_fma_f32 v[224:225], v[28:29], v[28:29], v[224:225]
	v_pk_fma_f32 v[224:225], v[30:31], v[30:31], v[224:225]
	v_lshlrev_b32_e32 v220, 16, v114
	v_and_b32_e32 v221, 0xffff0000, v114
	v_lshlrev_b32_e32 v222, 16, v115
	v_and_b32_e32 v223, 0xffff0000, v115
	v_pk_add_f32 v[32:33], v[32:33], v[220:221]
	v_pk_add_f32 v[34:35], v[34:35], v[222:223]
	v_pk_fma_f32 v[224:225], v[32:33], v[32:33], v[224:225]
	v_pk_fma_f32 v[224:225], v[34:35], v[34:35], v[224:225]
	v_add_f32_e32 v226, v224, v225
	ds_bpermute_b32 v227, v233, v226
	s_waitcnt lgkmcnt(0)
	v_add_f32_e32 v226, v226, v227
	ds_bpermute_b32 v227, v234, v226
	s_waitcnt lgkmcnt(0)
	v_add_f32_e32 v226, v226, v227
	v_fmamk_f32 v226, v226, 0x3c000000, v195
	v_rsq_f32_e32 v228, v226
	s_nop 0
	s_waitcnt vmcnt(16)
	v_pk_mul_f32 v[4:5], v[4:5], v[228:229] op_sel_hi:[1,0]
	v_pk_mul_f32 v[6:7], v[6:7], v[228:229] op_sel_hi:[1,0]
	v_lshlrev_b32_e32 v220, 16, v116
	v_and_b32_e32 v221, 0xffff0000, v116
	v_lshlrev_b32_e32 v222, 16, v117
	v_and_b32_e32 v223, 0xffff0000, v117
	v_pk_mul_f32 v[4:5], v[4:5], v[220:221]
	v_pk_mul_f32 v[6:7], v[6:7], v[222:223]
	v_cvt_pk_bf16_f32 v116, v4, v5
	v_cvt_pk_bf16_f32 v117, v6, v7
	v_pk_mul_f32 v[8:9], v[8:9], v[228:229] op_sel_hi:[1,0]
	v_pk_mul_f32 v[10:11], v[10:11], v[228:229] op_sel_hi:[1,0]
	v_lshlrev_b32_e32 v220, 16, v118
	v_and_b32_e32 v221, 0xffff0000, v118
	v_lshlrev_b32_e32 v222, 16, v119
	v_and_b32_e32 v223, 0xffff0000, v119
	v_pk_mul_f32 v[8:9], v[8:9], v[220:221]
	v_pk_mul_f32 v[10:11], v[10:11], v[222:223]
	v_cvt_pk_bf16_f32 v118, v8, v9
	v_cvt_pk_bf16_f32 v119, v10, v11
	global_store_dwordx4 v2, v[116:119], s[10:11]
	v_pk_mul_f32 v[12:13], v[12:13], v[228:229] op_sel_hi:[1,0]
	v_pk_mul_f32 v[14:15], v[14:15], v[228:229] op_sel_hi:[1,0]
	v_lshlrev_b32_e32 v220, 16, v120
	v_and_b32_e32 v221, 0xffff0000, v120
	v_lshlrev_b32_e32 v222, 16, v121
	v_and_b32_e32 v223, 0xffff0000, v121
	v_pk_mul_f32 v[12:13], v[12:13], v[220:221]
	v_pk_mul_f32 v[14:15], v[14:15], v[222:223]
	v_cvt_pk_bf16_f32 v120, v12, v13
	v_cvt_pk_bf16_f32 v121, v14, v15
	v_pk_mul_f32 v[16:17], v[16:17], v[228:229] op_sel_hi:[1,0]
	v_pk_mul_f32 v[18:19], v[18:19], v[228:229] op_sel_hi:[1,0]
	v_lshlrev_b32_e32 v220, 16, v122
	v_and_b32_e32 v221, 0xffff0000, v122
	v_lshlrev_b32_e32 v222, 16, v123
	v_and_b32_e32 v223, 0xffff0000, v123
	v_pk_mul_f32 v[16:17], v[16:17], v[220:221]
	v_pk_mul_f32 v[18:19], v[18:19], v[222:223]
	v_cvt_pk_bf16_f32 v122, v16, v17
	v_cvt_pk_bf16_f32 v123, v18, v19
	global_store_dwordx4 v2, v[120:123], s[10:11] offset:64
	v_pk_mul_f32 v[20:21], v[20:21], v[228:229] op_sel_hi:[1,0]
	v_pk_mul_f32 v[22:23], v[22:23], v[228:229] op_sel_hi:[1,0]
	v_lshlrev_b32_e32 v220, 16, v124
	v_and_b32_e32 v221, 0xffff0000, v124
	v_lshlrev_b32_e32 v222, 16, v125
	v_and_b32_e32 v223, 0xffff0000, v125
	v_pk_mul_f32 v[20:21], v[20:21], v[220:221]
	v_pk_mul_f32 v[22:23], v[22:23], v[222:223]
	v_cvt_pk_bf16_f32 v124, v20, v21
	v_cvt_pk_bf16_f32 v125, v22, v23
	v_pk_mul_f32 v[24:25], v[24:25], v[228:229] op_sel_hi:[1,0]
	v_pk_mul_f32 v[26:27], v[26:27], v[228:229] op_sel_hi:[1,0]
	v_lshlrev_b32_e32 v220, 16, v126
	v_and_b32_e32 v221, 0xffff0000, v126
	v_lshlrev_b32_e32 v222, 16, v127
	v_and_b32_e32 v223, 0xffff0000, v127
	v_pk_mul_f32 v[24:25], v[24:25], v[220:221]
	v_pk_mul_f32 v[26:27], v[26:27], v[222:223]
	v_cvt_pk_bf16_f32 v126, v24, v25
	v_cvt_pk_bf16_f32 v127, v26, v27
	global_store_dwordx4 v2, v[124:127], s[10:11] offset:128
	v_pk_mul_f32 v[28:29], v[28:29], v[228:229] op_sel_hi:[1,0]
	v_pk_mul_f32 v[30:31], v[30:31], v[228:229] op_sel_hi:[1,0]
	v_lshlrev_b32_e32 v220, 16, v128
	v_and_b32_e32 v221, 0xffff0000, v128
	v_lshlrev_b32_e32 v222, 16, v129
	v_and_b32_e32 v223, 0xffff0000, v129
	v_pk_mul_f32 v[28:29], v[28:29], v[220:221]
	v_pk_mul_f32 v[30:31], v[30:31], v[222:223]
	v_cvt_pk_bf16_f32 v128, v28, v29
	v_cvt_pk_bf16_f32 v129, v30, v31
	v_pk_mul_f32 v[32:33], v[32:33], v[228:229] op_sel_hi:[1,0]
	v_pk_mul_f32 v[34:35], v[34:35], v[228:229] op_sel_hi:[1,0]
	v_lshlrev_b32_e32 v220, 16, v130
	v_and_b32_e32 v221, 0xffff0000, v130
	v_lshlrev_b32_e32 v222, 16, v131
	v_and_b32_e32 v223, 0xffff0000, v131
	v_pk_mul_f32 v[32:33], v[32:33], v[220:221]
	v_pk_mul_f32 v[34:35], v[34:35], v[222:223]
	v_cvt_pk_bf16_f32 v130, v32, v33
	v_cvt_pk_bf16_f32 v131, v34, v35
	global_store_dwordx4 v2, v[128:131], s[10:11] offset:192
	s_add_u32 s10, s10, 0x8000
	s_addc_u32 s11, s11, 0
	global_load_dwordx4 v[84:87], v0, s[4:5]
	global_load_dwordx4 v[88:91], v0, s[4:5] offset:64
	global_load_dwordx4 v[92:95], v0, s[4:5] offset:128
	global_load_dwordx4 v[96:99], v0, s[4:5] offset:192
	global_load_dwordx4 v[100:103], v2, s[8:9]
	global_load_dwordx4 v[104:107], v2, s[8:9] offset:64
	global_load_dwordx4 v[108:111], v2, s[8:9] offset:128
	global_load_dwordx4 v[112:115], v2, s[8:9] offset:192
	global_load_dwordx4 v[116:119], v1, s[6:7]
	global_load_dwordx4 v[120:123], v1, s[6:7] offset:64
	global_load_dwordx4 v[124:127], v1, s[6:7] offset:128
	global_load_dwordx4 v[128:131], v1, s[6:7] offset:192
	s_add_u32 s4, s4, 0x6000
	s_addc_u32 s5, s5, 0
	s_add_u32 s6, s6, 0x6000
	s_addc_u32 s7, s7, 0
	s_add_u32 s8, s8, 0x8000
	s_addc_u32 s9, s9, 0
	s_cmp_eq_u32 s40, 0
	s_cbranch_scc1 .Lfix_nomm_tb
	s_waitcnt vmcnt(24)
	ds_read_b128 v[132:135], v232 offset:0
	ds_read_b128 v[136:139], v232 offset:64
	ds_read_b128 v[140:143], v232 offset:128
	ds_read_b128 v[144:147], v232 offset:192
	ds_read_b128 v[148:151], v232 offset:1088
	ds_read_b128 v[152:155], v232 offset:1152
	ds_read_b128 v[172:175], v232 offset:1216
	ds_read_b128 v[176:179], v232 offset:1280
	ds_read_b128 v[180:183], v232 offset:8704
	ds_read_b128 v[184:187], v232 offset:8768
	ds_read_b128 v[188:191], v232 offset:8832
	ds_read_b128 v[200:203], v232 offset:8896
	s_waitcnt lgkmcnt(8)
	v_mfma_f32_16x16x32_bf16 v[4:7], v[132:135], v[36:39], 0
	v_mfma_f32_16x16x32_bf16 v[4:7], v[136:139], v[40:43], v[4:7]
	v_mfma_f32_16x16x32_bf16 v[4:7], v[140:143], v[44:47], v[4:7]
	v_mfma_f32_16x16x32_bf16 v[4:7], v[144:147], v[48:51], v[4:7]
	ds_read_b128 v[132:135], v232 offset:9792
	ds_read_b128 v[136:139], v232 offset:9856
	ds_read_b128 v[140:143], v232 offset:9920
	ds_read_b128 v[144:147], v232 offset:9984
	s_waitcnt lgkmcnt(8)
	v_mfma_f32_16x16x32_bf16 v[8:11], v[148:151], v[36:39], 0
	v_mfma_f32_16x16x32_bf16 v[8:11], v[152:155], v[40:43], v[8:11]
	v_mfma_f32_16x16x32_bf16 v[8:11], v[172:175], v[44:47], v[8:11]
	v_mfma_f32_16x16x32_bf16 v[8:11], v[176:179], v[48:51], v[8:11]
	ds_read_b128 v[148:151], v232 offset:17408
	ds_read_b128 v[152:155], v232 offset:17472
	ds_read_b128 v[172:175], v232 offset:17536
	ds_read_b128 v[176:179], v232 offset:17600
	s_waitcnt lgkmcnt(8)
	v_mfma_f32_16x16x32_bf16 v[12:15], v[180:183], v[36:39], 0
	v_mfma_f32_16x16x32_bf16 v[12:15], v[184:187], v[40:43], v[12:15]
	v_mfma_f32_16x16x32_bf16 v[12:15], v[188:191], v[44:47], v[12:15]
	v_mfma_f32_16x16x32_bf16 v[12:15], v[200:203], v[48:51], v[12:15]
	ds_read_b128 v[180:183], v232 offset:18496
	ds_read_b128 v[184:187], v232 offset:18560
	ds_read_b128 v[188:191], v232 offset:18624
	ds_read_b128 v[200:203], v232 offset:18688
	s_waitcnt lgkmcnt(8)
	v_mfma_f32_16x16x32_bf16 v[16:19], v[132:135], v[36:39], 0
	v_mfma_f32_16x16x32_bf16 v[16:19], v[136:139], v[40:43], v[16:19]
	v_mfma_f32_16x16x32_bf16 v[16:19], v[140:143], v[44:47], v[16:19]
	v_mfma_f32_16x16x32_bf16 v[16:19], v[144:147], v[48:51], v[16:19]
	ds_read_b128 v[132:135], v232 offset:26112
	ds_read_b128 v[136:139], v232 offset:26176
	ds_read_b128 v[140:143], v232 offset:26240
	ds_read_b128 v[144:147], v232 offset:26304
	s_waitcnt lgkmcnt(8)
	v_mfma_f32_16x16x32_bf16 v[20:23], v[148:151], v[36:39], 0
	v_mfma_f32_16x16x32_bf16 v[20:23], v[152:155], v[40:43], v[20:23]
	v_mfma_f32_16x16x32_bf16 v[20:23], v[172:175], v[44:47], v[20:23]
	v_mfma_f32_16x16x32_bf16 v[20:23], v[176:179], v[48:51], v[20:23]
	ds_read_b128 v[148:151], v232 offset:27200
	ds_read_b128 v[152:155], v232 offset:27264
	ds_read_b128 v[172:175], v232 offset:27328
	ds_read_b128 v[176:179], v232 offset:27392
	s_waitcnt lgkmcnt(8)
	v_mfma_f32_16x16x32_bf16 v[24:27], v[180:183], v[36:39], 0
	v_mfma_f32_16x16x32_bf16 v[24:27], v[184:187], v[40:43], v[24:27]
	v_mfma_f32_16x16x32_bf16 v[24:27], v[188:191], v[44:47], v[24:27]
	v_mfma_f32_16x16x32_bf16 v[24:27], v[200:203], v[48:51], v[24:27]
	s_waitcnt lgkmcnt(4)
	v_mfma_f32_16x16x32_bf16 v[28:31], v[132:135], v[36:39], 0
	v_mfma_f32_16x16x32_bf16 v[28:31], v[136:139], v[40:43], v[28:31]
	v_mfma_f32_16x16x32_bf16 v[28:31], v[140:143], v[44:47], v[28:31]
	v_mfma_f32_16x16x32_bf16 v[28:31], v[144:147], v[48:51], v[28:31]
	s_waitcnt lgkmcnt(0)
	v_mfma_f32_16x16x32_bf16 v[32:35], v[148:151], v[36:39], 0
	v_mfma_f32_16x16x32_bf16 v[32:35], v[152:155], v[40:43], v[32:35]
	v_mfma_f32_16x16x32_bf16 v[32:35], v[172:175], v[44:47], v[32:35]
	v_mfma_f32_16x16x32_bf16 v[32:35], v[176:179], v[48:51], v[32:35]
	s_branch .Lfix_mmdone_tb

.Lfix_mmdone_tb:
	s_waitcnt vmcnt(20)
	v_lshlrev_b32_e32 v220, 16, v52
	v_and_b32_e32 v221, 0xffff0000, v52
	v_lshlrev_b32_e32 v222, 16, v53
	v_and_b32_e32 v223, 0xffff0000, v53
	v_pk_add_f32 v[4:5], v[4:5], v[220:221]
	v_pk_add_f32 v[6:7], v[6:7], v[222:223]
	v_pk_mul_f32 v[224:225], v[4:5], v[4:5]
	v_pk_fma_f32 v[224:225], v[6:7], v[6:7], v[224:225]
	v_lshlrev_b32_e32 v220, 16, v54
	v_and_b32_e32 v221, 0xffff0000, v54
	v_lshlrev_b32_e32 v222, 16, v55
	v_and_b32_e32 v223, 0xffff0000, v55
	v_pk_add_f32 v[8:9], v[8:9], v[220:221]
	v_pk_add_f32 v[10:11], v[10:11], v[222:223]
	v_pk_fma_f32 v[224:225], v[8:9], v[8:9], v[224:225]
	v_pk_fma_f32 v[224:225], v[10:11], v[10:11], v[224:225]
	v_lshlrev_b32_e32 v220, 16, v56
	v_and_b32_e32 v221, 0xffff0000, v56
	v_lshlrev_b32_e32 v222, 16, v57
	v_and_b32_e32 v223, 0xffff0000, v57
	v_pk_add_f32 v[12:13], v[12:13], v[220:221]
	v_pk_add_f32 v[14:15], v[14:15], v[222:223]
	v_pk_fma_f32 v[224:225], v[12:13], v[12:13], v[224:225]
	v_pk_fma_f32 v[224:225], v[14:15], v[14:15], v[224:225]
	v_lshlrev_b32_e32 v220, 16, v58
	v_and_b32_e32 v221, 0xffff0000, v58
	v_lshlrev_b32_e32 v222, 16, v59
	v_and_b32_e32 v223, 0xffff0000, v59
	v_pk_add_f32 v[16:17], v[16:17], v[220:221]
	v_pk_add_f32 v[18:19], v[18:19], v[222:223]
	v_pk_fma_f32 v[224:225], v[16:17], v[16:17], v[224:225]
	v_pk_fma_f32 v[224:225], v[18:19], v[18:19], v[224:225]
	v_lshlrev_b32_e32 v220, 16, v60
	v_and_b32_e32 v221, 0xffff0000, v60
	v_lshlrev_b32_e32 v222, 16, v61
	v_and_b32_e32 v223, 0xffff0000, v61
	v_pk_add_f32 v[20:21], v[20:21], v[220:221]
	v_pk_add_f32 v[22:23], v[22:23], v[222:223]
	v_pk_fma_f32 v[224:225], v[20:21], v[20:21], v[224:225]
	v_pk_fma_f32 v[224:225], v[22:23], v[22:23], v[224:225]
	v_lshlrev_b32_e32 v220, 16, v62
	v_and_b32_e32 v221, 0xffff0000, v62
	v_lshlrev_b32_e32 v222, 16, v63
	v_and_b32_e32 v223, 0xffff0000, v63
	v_pk_add_f32 v[24:25], v[24:25], v[220:221]
	v_pk_add_f32 v[26:27], v[26:27], v[222:223]
	v_pk_fma_f32 v[224:225], v[24:25], v[24:25], v[224:225]
	v_pk_fma_f32 v[224:225], v[26:27], v[26:27], v[224:225]
	v_lshlrev_b32_e32 v220, 16, v64
	v_and_b32_e32 v221, 0xffff0000, v64
	v_lshlrev_b32_e32 v222, 16, v65
	v_and_b32_e32 v223, 0xffff0000, v65
	v_pk_add_f32 v[28:29], v[28:29], v[220:221]
	v_pk_add_f32 v[30:31], v[30:31], v[222:223]
	v_pk_fma_f32 v[224:225], v[28:29], v[28:29], v[224:225]
	v_pk_fma_f32 v[224:225], v[30:31], v[30:31], v[224:225]
	v_lshlrev_b32_e32 v220, 16, v66
	v_and_b32_e32 v221, 0xffff0000, v66
	v_lshlrev_b32_e32 v222, 16, v67
	v_and_b32_e32 v223, 0xffff0000, v67
	v_pk_add_f32 v[32:33], v[32:33], v[220:221]
	v_pk_add_f32 v[34:35], v[34:35], v[222:223]
	v_pk_fma_f32 v[224:225], v[32:33], v[32:33], v[224:225]
	v_pk_fma_f32 v[224:225], v[34:35], v[34:35], v[224:225]
	v_add_f32_e32 v226, v224, v225
	ds_bpermute_b32 v227, v233, v226
	s_waitcnt lgkmcnt(0)
	v_add_f32_e32 v226, v226, v227
	ds_bpermute_b32 v227, v234, v226
	s_waitcnt lgkmcnt(0)
	v_add_f32_e32 v226, v226, v227
	v_fmamk_f32 v226, v226, 0x3c000000, v195
	v_rsq_f32_e32 v228, v226
	s_nop 0
	s_waitcnt vmcnt(16)
	v_pk_mul_f32 v[4:5], v[4:5], v[228:229] op_sel_hi:[1,0]
	v_pk_mul_f32 v[6:7], v[6:7], v[228:229] op_sel_hi:[1,0]
	v_lshlrev_b32_e32 v220, 16, v68
	v_and_b32_e32 v221, 0xffff0000, v68
	v_lshlrev_b32_e32 v222, 16, v69
	v_and_b32_e32 v223, 0xffff0000, v69
	v_pk_mul_f32 v[4:5], v[4:5], v[220:221]
	v_pk_mul_f32 v[6:7], v[6:7], v[222:223]
	v_cvt_pk_bf16_f32 v68, v4, v5
	v_cvt_pk_bf16_f32 v69, v6, v7
	v_pk_mul_f32 v[8:9], v[8:9], v[228:229] op_sel_hi:[1,0]
	v_pk_mul_f32 v[10:11], v[10:11], v[228:229] op_sel_hi:[1,0]
	v_lshlrev_b32_e32 v220, 16, v70
	v_and_b32_e32 v221, 0xffff0000, v70
	v_lshlrev_b32_e32 v222, 16, v71
	v_and_b32_e32 v223, 0xffff0000, v71
	v_pk_mul_f32 v[8:9], v[8:9], v[220:221]
	v_pk_mul_f32 v[10:11], v[10:11], v[222:223]
	v_cvt_pk_bf16_f32 v70, v8, v9
	v_cvt_pk_bf16_f32 v71, v10, v11
	global_store_dwordx4 v2, v[68:71], s[10:11]
	v_pk_mul_f32 v[12:13], v[12:13], v[228:229] op_sel_hi:[1,0]
	v_pk_mul_f32 v[14:15], v[14:15], v[228:229] op_sel_hi:[1,0]
	v_lshlrev_b32_e32 v220, 16, v72
	v_and_b32_e32 v221, 0xffff0000, v72
	v_lshlrev_b32_e32 v222, 16, v73
	v_and_b32_e32 v223, 0xffff0000, v73
	v_pk_mul_f32 v[12:13], v[12:13], v[220:221]
	v_pk_mul_f32 v[14:15], v[14:15], v[222:223]
	v_cvt_pk_bf16_f32 v72, v12, v13
	v_cvt_pk_bf16_f32 v73, v14, v15
	v_pk_mul_f32 v[16:17], v[16:17], v[228:229] op_sel_hi:[1,0]
	v_pk_mul_f32 v[18:19], v[18:19], v[228:229] op_sel_hi:[1,0]
	v_lshlrev_b32_e32 v220, 16, v74
	v_and_b32_e32 v221, 0xffff0000, v74
	v_lshlrev_b32_e32 v222, 16, v75
	v_and_b32_e32 v223, 0xffff0000, v75
	v_pk_mul_f32 v[16:17], v[16:17], v[220:221]
	v_pk_mul_f32 v[18:19], v[18:19], v[222:223]
	v_cvt_pk_bf16_f32 v74, v16, v17
	v_cvt_pk_bf16_f32 v75, v18, v19
	global_store_dwordx4 v2, v[72:75], s[10:11] offset:64
	v_pk_mul_f32 v[20:21], v[20:21], v[228:229] op_sel_hi:[1,0]
	v_pk_mul_f32 v[22:23], v[22:23], v[228:229] op_sel_hi:[1,0]
	v_lshlrev_b32_e32 v220, 16, v76
	v_and_b32_e32 v221, 0xffff0000, v76
	v_lshlrev_b32_e32 v222, 16, v77
	v_and_b32_e32 v223, 0xffff0000, v77
	v_pk_mul_f32 v[20:21], v[20:21], v[220:221]
	v_pk_mul_f32 v[22:23], v[22:23], v[222:223]
	v_cvt_pk_bf16_f32 v76, v20, v21
	v_cvt_pk_bf16_f32 v77, v22, v23
	v_pk_mul_f32 v[24:25], v[24:25], v[228:229] op_sel_hi:[1,0]
	v_pk_mul_f32 v[26:27], v[26:27], v[228:229] op_sel_hi:[1,0]
	v_lshlrev_b32_e32 v220, 16, v78
	v_and_b32_e32 v221, 0xffff0000, v78
	v_lshlrev_b32_e32 v222, 16, v79
	v_and_b32_e32 v223, 0xffff0000, v79
	v_pk_mul_f32 v[24:25], v[24:25], v[220:221]
	v_pk_mul_f32 v[26:27], v[26:27], v[222:223]
	v_cvt_pk_bf16_f32 v78, v24, v25
	v_cvt_pk_bf16_f32 v79, v26, v27
	global_store_dwordx4 v2, v[76:79], s[10:11] offset:128
	v_pk_mul_f32 v[28:29], v[28:29], v[228:229] op_sel_hi:[1,0]
	v_pk_mul_f32 v[30:31], v[30:31], v[228:229] op_sel_hi:[1,0]
	v_lshlrev_b32_e32 v220, 16, v80
	v_and_b32_e32 v221, 0xffff0000, v80
	v_lshlrev_b32_e32 v222, 16, v81
	v_and_b32_e32 v223, 0xffff0000, v81
	v_pk_mul_f32 v[28:29], v[28:29], v[220:221]
	v_pk_mul_f32 v[30:31], v[30:31], v[222:223]
	v_cvt_pk_bf16_f32 v80, v28, v29
	v_cvt_pk_bf16_f32 v81, v30, v31
	v_pk_mul_f32 v[32:33], v[32:33], v[228:229] op_sel_hi:[1,0]
	v_pk_mul_f32 v[34:35], v[34:35], v[228:229] op_sel_hi:[1,0]
	v_lshlrev_b32_e32 v220, 16, v82
	v_and_b32_e32 v221, 0xffff0000, v82
	v_lshlrev_b32_e32 v222, 16, v83
	v_and_b32_e32 v223, 0xffff0000, v83
	v_pk_mul_f32 v[32:33], v[32:33], v[220:221]
	v_pk_mul_f32 v[34:35], v[34:35], v[222:223]
	v_cvt_pk_bf16_f32 v82, v32, v33
	v_cvt_pk_bf16_f32 v83, v34, v35
	global_store_dwordx4 v2, v[80:83], s[10:11] offset:192
	s_add_u32 s10, s10, 0x8000
	s_addc_u32 s11, s11, 0
	s_add_i32 s13, s13, -1
	s_cmp_lg_u32 s13, 0
	s_cbranch_scc1 .Lfix_loop
	s_cmp_eq_u32 s40, 0
	s_cbranch_scc1 .Lfix_nomm_t7
	s_waitcnt vmcnt(12)
	ds_read_b128 v[132:135], v232 offset:0
	ds_read_b128 v[136:139], v232 offset:64
	ds_read_b128 v[140:143], v232 offset:128
	ds_read_b128 v[144:147], v232 offset:192
	ds_read_b128 v[148:151], v232 offset:1088
	ds_read_b128 v[152:155], v232 offset:1152
	ds_read_b128 v[172:175], v232 offset:1216
	ds_read_b128 v[176:179], v232 offset:1280
	ds_read_b128 v[180:183], v232 offset:8704
	ds_read_b128 v[184:187], v232 offset:8768
	ds_read_b128 v[188:191], v232 offset:8832
	ds_read_b128 v[200:203], v232 offset:8896
	s_waitcnt lgkmcnt(8)
	v_mfma_f32_16x16x32_bf16 v[4:7], v[132:135], v[84:87], 0
	v_mfma_f32_16x16x32_bf16 v[4:7], v[136:139], v[88:91], v[4:7]
	v_mfma_f32_16x16x32_bf16 v[4:7], v[140:143], v[92:95], v[4:7]
	v_mfma_f32_16x16x32_bf16 v[4:7], v[144:147], v[96:99], v[4:7]
	ds_read_b128 v[132:135], v232 offset:9792
	ds_read_b128 v[136:139], v232 offset:9856
	ds_read_b128 v[140:143], v232 offset:9920
	ds_read_b128 v[144:147], v232 offset:9984
	s_waitcnt lgkmcnt(8)
	v_mfma_f32_16x16x32_bf16 v[8:11], v[148:151], v[84:87], 0
	v_mfma_f32_16x16x32_bf16 v[8:11], v[152:155], v[88:91], v[8:11]
	v_mfma_f32_16x16x32_bf16 v[8:11], v[172:175], v[92:95], v[8:11]
	v_mfma_f32_16x16x32_bf16 v[8:11], v[176:179], v[96:99], v[8:11]
	ds_read_b128 v[148:151], v232 offset:17408
	ds_read_b128 v[152:155], v232 offset:17472
	ds_read_b128 v[172:175], v232 offset:17536
	ds_read_b128 v[176:179], v232 offset:17600
	s_waitcnt lgkmcnt(8)
	v_mfma_f32_16x16x32_bf16 v[12:15], v[180:183], v[84:87], 0
	v_mfma_f32_16x16x32_bf16 v[12:15], v[184:187], v[88:91], v[12:15]
	v_mfma_f32_16x16x32_bf16 v[12:15], v[188:191], v[92:95], v[12:15]
	v_mfma_f32_16x16x32_bf16 v[12:15], v[200:203], v[96:99], v[12:15]
	ds_read_b128 v[180:183], v232 offset:18496
	ds_read_b128 v[184:187], v232 offset:18560
	ds_read_b128 v[188:191], v232 offset:18624
	ds_read_b128 v[200:203], v232 offset:18688
	s_waitcnt lgkmcnt(8)
	v_mfma_f32_16x16x32_bf16 v[16:19], v[132:135], v[84:87], 0
	v_mfma_f32_16x16x32_bf16 v[16:19], v[136:139], v[88:91], v[16:19]
	v_mfma_f32_16x16x32_bf16 v[16:19], v[140:143], v[92:95], v[16:19]
	v_mfma_f32_16x16x32_bf16 v[16:19], v[144:147], v[96:99], v[16:19]
	ds_read_b128 v[132:135], v232 offset:26112
	ds_read_b128 v[136:139], v232 offset:26176
	ds_read_b128 v[140:143], v232 offset:26240
	ds_read_b128 v[144:147], v232 offset:26304
	s_waitcnt lgkmcnt(8)
	v_mfma_f32_16x16x32_bf16 v[20:23], v[148:151], v[84:87], 0
	v_mfma_f32_16x16x32_bf16 v[20:23], v[152:155], v[88:91], v[20:23]
	v_mfma_f32_16x16x32_bf16 v[20:23], v[172:175], v[92:95], v[20:23]
	v_mfma_f32_16x16x32_bf16 v[20:23], v[176:179], v[96:99], v[20:23]
	ds_read_b128 v[148:151], v232 offset:27200
	ds_read_b128 v[152:155], v232 offset:27264
	ds_read_b128 v[172:175], v232 offset:27328
	ds_read_b128 v[176:179], v232 offset:27392
	s_waitcnt lgkmcnt(8)
	v_mfma_f32_16x16x32_bf16 v[24:27], v[180:183], v[84:87], 0
	v_mfma_f32_16x16x32_bf16 v[24:27], v[184:187], v[88:91], v[24:27]
	v_mfma_f32_16x16x32_bf16 v[24:27], v[188:191], v[92:95], v[24:27]
	v_mfma_f32_16x16x32_bf16 v[24:27], v[200:203], v[96:99], v[24:27]
	s_waitcnt lgkmcnt(4)
	v_mfma_f32_16x16x32_bf16 v[28:31], v[132:135], v[84:87], 0
	v_mfma_f32_16x16x32_bf16 v[28:31], v[136:139], v[88:91], v[28:31]
	v_mfma_f32_16x16x32_bf16 v[28:31], v[140:143], v[92:95], v[28:31]
	v_mfma_f32_16x16x32_bf16 v[28:31], v[144:147], v[96:99], v[28:31]
	s_waitcnt lgkmcnt(0)
	v_mfma_f32_16x16x32_bf16 v[32:35], v[148:151], v[84:87], 0
	v_mfma_f32_16x16x32_bf16 v[32:35], v[152:155], v[88:91], v[32:35]
	v_mfma_f32_16x16x32_bf16 v[32:35], v[172:175], v[92:95], v[32:35]
	v_mfma_f32_16x16x32_bf16 v[32:35], v[176:179], v[96:99], v[32:35]
	s_branch .Lfix_mmdone_t7

.Lfix_mmdone_t7:
	s_waitcnt vmcnt(8)
	v_lshlrev_b32_e32 v220, 16, v100
	v_and_b32_e32 v221, 0xffff0000, v100
	v_lshlrev_b32_e32 v222, 16, v101
	v_and_b32_e32 v223, 0xffff0000, v101
	v_pk_add_f32 v[4:5], v[4:5], v[220:221]
	v_pk_add_f32 v[6:7], v[6:7], v[222:223]
	v_pk_mul_f32 v[224:225], v[4:5], v[4:5]
	v_pk_fma_f32 v[224:225], v[6:7], v[6:7], v[224:225]
	v_lshlrev_b32_e32 v220, 16, v102
	v_and_b32_e32 v221, 0xffff0000, v102
	v_lshlrev_b32_e32 v222, 16, v103
	v_and_b32_e32 v223, 0xffff0000, v103
	v_pk_add_f32 v[8:9], v[8:9], v[220:221]
	v_pk_add_f32 v[10:11], v[10:11], v[222:223]
	v_pk_fma_f32 v[224:225], v[8:9], v[8:9], v[224:225]
	v_pk_fma_f32 v[224:225], v[10:11], v[10:11], v[224:225]
	v_lshlrev_b32_e32 v220, 16, v104
	v_and_b32_e32 v221, 0xffff0000, v104
	v_lshlrev_b32_e32 v222, 16, v105
	v_and_b32_e32 v223, 0xffff0000, v105
	v_pk_add_f32 v[12:13], v[12:13], v[220:221]
	v_pk_add_f32 v[14:15], v[14:15], v[222:223]
	v_pk_fma_f32 v[224:225], v[12:13], v[12:13], v[224:225]
	v_pk_fma_f32 v[224:225], v[14:15], v[14:15], v[224:225]
	v_lshlrev_b32_e32 v220, 16, v106
	v_and_b32_e32 v221, 0xffff0000, v106
	v_lshlrev_b32_e32 v222, 16, v107
	v_and_b32_e32 v223, 0xffff0000, v107
	v_pk_add_f32 v[16:17], v[16:17], v[220:221]
	v_pk_add_f32 v[18:19], v[18:19], v[222:223]
	v_pk_fma_f32 v[224:225], v[16:17], v[16:17], v[224:225]
	v_pk_fma_f32 v[224:225], v[18:19], v[18:19], v[224:225]
	v_lshlrev_b32_e32 v220, 16, v108
	v_and_b32_e32 v221, 0xffff0000, v108
	v_lshlrev_b32_e32 v222, 16, v109
	v_and_b32_e32 v223, 0xffff0000, v109
	v_pk_add_f32 v[20:21], v[20:21], v[220:221]
	v_pk_add_f32 v[22:23], v[22:23], v[222:223]
	v_pk_fma_f32 v[224:225], v[20:21], v[20:21], v[224:225]
	v_pk_fma_f32 v[224:225], v[22:23], v[22:23], v[224:225]
	v_lshlrev_b32_e32 v220, 16, v110
	v_and_b32_e32 v221, 0xffff0000, v110
	v_lshlrev_b32_e32 v222, 16, v111
	v_and_b32_e32 v223, 0xffff0000, v111
	v_pk_add_f32 v[24:25], v[24:25], v[220:221]
	v_pk_add_f32 v[26:27], v[26:27], v[222:223]
	v_pk_fma_f32 v[224:225], v[24:25], v[24:25], v[224:225]
	v_pk_fma_f32 v[224:225], v[26:27], v[26:27], v[224:225]
	v_lshlrev_b32_e32 v220, 16, v112
	v_and_b32_e32 v221, 0xffff0000, v112
	v_lshlrev_b32_e32 v222, 16, v113
	v_and_b32_e32 v223, 0xffff0000, v113
	v_pk_add_f32 v[28:29], v[28:29], v[220:221]
	v_pk_add_f32 v[30:31], v[30:31], v[222:223]
	v_pk_fma_f32 v[224:225], v[28:29], v[28:29], v[224:225]
	v_pk_fma_f32 v[224:225], v[30:31], v[30:31], v[224:225]
	v_lshlrev_b32_e32 v220, 16, v114
	v_and_b32_e32 v221, 0xffff0000, v114
	v_lshlrev_b32_e32 v222, 16, v115
	v_and_b32_e32 v223, 0xffff0000, v115
	v_pk_add_f32 v[32:33], v[32:33], v[220:221]
	v_pk_add_f32 v[34:35], v[34:35], v[222:223]
	v_pk_fma_f32 v[224:225], v[32:33], v[32:33], v[224:225]
	v_pk_fma_f32 v[224:225], v[34:35], v[34:35], v[224:225]
	v_add_f32_e32 v226, v224, v225
	ds_bpermute_b32 v227, v233, v226
	s_waitcnt lgkmcnt(0)
	v_add_f32_e32 v226, v226, v227
	ds_bpermute_b32 v227, v234, v226
	s_waitcnt lgkmcnt(0)
	v_add_f32_e32 v226, v226, v227
	v_fmamk_f32 v226, v226, 0x3c000000, v195
	v_rsq_f32_e32 v228, v226
	s_nop 0
	s_waitcnt vmcnt(4)
	v_pk_mul_f32 v[4:5], v[4:5], v[228:229] op_sel_hi:[1,0]
	v_pk_mul_f32 v[6:7], v[6:7], v[228:229] op_sel_hi:[1,0]
	v_lshlrev_b32_e32 v220, 16, v116
	v_and_b32_e32 v221, 0xffff0000, v116
	v_lshlrev_b32_e32 v222, 16, v117
	v_and_b32_e32 v223, 0xffff0000, v117
	v_pk_mul_f32 v[4:5], v[4:5], v[220:221]
	v_pk_mul_f32 v[6:7], v[6:7], v[222:223]
	v_cvt_pk_bf16_f32 v116, v4, v5
	v_cvt_pk_bf16_f32 v117, v6, v7
	v_pk_mul_f32 v[8:9], v[8:9], v[228:229] op_sel_hi:[1,0]
	v_pk_mul_f32 v[10:11], v[10:11], v[228:229] op_sel_hi:[1,0]
	v_lshlrev_b32_e32 v220, 16, v118
	v_and_b32_e32 v221, 0xffff0000, v118
	v_lshlrev_b32_e32 v222, 16, v119
	v_and_b32_e32 v223, 0xffff0000, v119
	v_pk_mul_f32 v[8:9], v[8:9], v[220:221]
	v_pk_mul_f32 v[10:11], v[10:11], v[222:223]
	v_cvt_pk_bf16_f32 v118, v8, v9
	v_cvt_pk_bf16_f32 v119, v10, v11
	global_store_dwordx4 v2, v[116:119], s[10:11]
	v_pk_mul_f32 v[12:13], v[12:13], v[228:229] op_sel_hi:[1,0]
	v_pk_mul_f32 v[14:15], v[14:15], v[228:229] op_sel_hi:[1,0]
	v_lshlrev_b32_e32 v220, 16, v120
	v_and_b32_e32 v221, 0xffff0000, v120
	v_lshlrev_b32_e32 v222, 16, v121
	v_and_b32_e32 v223, 0xffff0000, v121
	v_pk_mul_f32 v[12:13], v[12:13], v[220:221]
	v_pk_mul_f32 v[14:15], v[14:15], v[222:223]
	v_cvt_pk_bf16_f32 v120, v12, v13
	v_cvt_pk_bf16_f32 v121, v14, v15
	v_pk_mul_f32 v[16:17], v[16:17], v[228:229] op_sel_hi:[1,0]
	v_pk_mul_f32 v[18:19], v[18:19], v[228:229] op_sel_hi:[1,0]
	v_lshlrev_b32_e32 v220, 16, v122
	v_and_b32_e32 v221, 0xffff0000, v122
	v_lshlrev_b32_e32 v222, 16, v123
	v_and_b32_e32 v223, 0xffff0000, v123
	v_pk_mul_f32 v[16:17], v[16:17], v[220:221]
	v_pk_mul_f32 v[18:19], v[18:19], v[222:223]
	v_cvt_pk_bf16_f32 v122, v16, v17
	v_cvt_pk_bf16_f32 v123, v18, v19
	global_store_dwordx4 v2, v[120:123], s[10:11] offset:64
	v_pk_mul_f32 v[20:21], v[20:21], v[228:229] op_sel_hi:[1,0]
	v_pk_mul_f32 v[22:23], v[22:23], v[228:229] op_sel_hi:[1,0]
	v_lshlrev_b32_e32 v220, 16, v124
	v_and_b32_e32 v221, 0xffff0000, v124
	v_lshlrev_b32_e32 v222, 16, v125
	v_and_b32_e32 v223, 0xffff0000, v125
	v_pk_mul_f32 v[20:21], v[20:21], v[220:221]
	v_pk_mul_f32 v[22:23], v[22:23], v[222:223]
	v_cvt_pk_bf16_f32 v124, v20, v21
	v_cvt_pk_bf16_f32 v125, v22, v23
	v_pk_mul_f32 v[24:25], v[24:25], v[228:229] op_sel_hi:[1,0]
	v_pk_mul_f32 v[26:27], v[26:27], v[228:229] op_sel_hi:[1,0]
	v_lshlrev_b32_e32 v220, 16, v126
	v_and_b32_e32 v221, 0xffff0000, v126
	v_lshlrev_b32_e32 v222, 16, v127
	v_and_b32_e32 v223, 0xffff0000, v127
	v_pk_mul_f32 v[24:25], v[24:25], v[220:221]
	v_pk_mul_f32 v[26:27], v[26:27], v[222:223]
	v_cvt_pk_bf16_f32 v126, v24, v25
	v_cvt_pk_bf16_f32 v127, v26, v27
	global_store_dwordx4 v2, v[124:127], s[10:11] offset:128
	v_pk_mul_f32 v[28:29], v[28:29], v[228:229] op_sel_hi:[1,0]
	v_pk_mul_f32 v[30:31], v[30:31], v[228:229] op_sel_hi:[1,0]
	v_lshlrev_b32_e32 v220, 16, v128
	v_and_b32_e32 v221, 0xffff0000, v128
	v_lshlrev_b32_e32 v222, 16, v129
	v_and_b32_e32 v223, 0xffff0000, v129
	v_pk_mul_f32 v[28:29], v[28:29], v[220:221]
	v_pk_mul_f32 v[30:31], v[30:31], v[222:223]
	v_cvt_pk_bf16_f32 v128, v28, v29
	v_cvt_pk_bf16_f32 v129, v30, v31
	v_pk_mul_f32 v[32:33], v[32:33], v[228:229] op_sel_hi:[1,0]
	v_pk_mul_f32 v[34:35], v[34:35], v[228:229] op_sel_hi:[1,0]
	v_lshlrev_b32_e32 v220, 16, v130
	v_and_b32_e32 v221, 0xffff0000, v130
	v_lshlrev_b32_e32 v222, 16, v131
	v_and_b32_e32 v223, 0xffff0000, v131
	v_pk_mul_f32 v[32:33], v[32:33], v[220:221]
	v_pk_mul_f32 v[34:35], v[34:35], v[222:223]
	v_cvt_pk_bf16_f32 v130, v32, v33
	v_cvt_pk_bf16_f32 v131, v34, v35
	global_store_dwordx4 v2, v[128:131], s[10:11] offset:192
	s_add_u32 s10, s10, 0x8000
	s_addc_u32 s11, s11, 0
